# static s_setprio 1 for waves 4-7 during P3 (attention + ssm_local), reset to 0 at the phase end
# baseline (speedup 1.0000x reference)
.LBB0_294:
	s_cmp_ge_u32 s3, 4
	s_cbranch_scc0 .Lprio_skip0
	s_setprio 1

.LBB0_327:
	s_setprio 0
	s_cmp_gt_u32 s81, 4
	s_waitcnt lgkmcnt(0)
	s_barrier
	s_cbranch_scc0 .LBB0_381
	s_waitcnt vmcnt(0)
	s_barrier
	s_and_saveexec_b64 s[0:1], s[44:45]
	s_cbranch_execz .LBB0_380
	s_add_u32 s4, s62, 0x3300200
	s_addc_u32 s5, s63, 0
	s_add_i32 s6, 0, 0x23fc0
	v_mov_b32_e32 v0, s6
	s_waitcnt vmcnt(0) expcnt(0) lgkmcnt(0)
	ds_read_b32 v2, v0
	s_add_i32 s6, 0, 0x23fc4
	v_mov_b32_e32 v0, s6
	ds_read_b32 v0, v0
	s_waitcnt lgkmcnt(1)
	v_cmp_ne_u32_e32 vcc, 0, v2
	s_cbranch_vccnz .LBB0_344
	s_add_u32 s6, s62, 0x3300400
	s_addc_u32 s7, s63, 0
	s_add_u32 s8, s62, 0x3300500
	s_addc_u32 s9, s63, 0
	s_add_u32 s10, s62, 0x3300600
	s_addc_u32 s11, s63, 0
	s_add_u32 s12, s62, 0x3300700
	s_addc_u32 s13, s63, 0
	s_add_u32 s14, s62, 0x3300800
	s_addc_u32 s15, s63, 0
	s_add_u32 s16, s62, 0x3300900
	s_addc_u32 s17, s63, 0
	s_add_u32 s18, s62, 0x3300a00
	s_addc_u32 s19, s63, 0
	s_add_u32 s20, s62, 0x3300b00
	s_addc_u32 s21, s63, 0
	s_add_u32 s22, s62, 0x3300c00
	s_addc_u32 s23, s63, 0
	s_add_u32 s24, s62, 0x3300d00
	s_addc_u32 s25, s63, 0
	s_add_u32 s26, s62, 0x3300e00
	s_addc_u32 s27, s63, 0
	s_add_u32 s28, s62, 0x3300f00
	s_addc_u32 s29, s63, 0
	s_add_u32 s30, s62, 0x3301000
	s_addc_u32 s31, s63, 0
	s_add_u32 s34, s62, 0x3301100
	s_addc_u32 s35, s63, 0
	s_add_u32 s36, s62, 0x3301200
	s_addc_u32 s37, s63, 0
	s_mul_i32 s56, s83, s82
	s_add_u32 s38, s62, 0x3301300
	s_mul_i32 s56, s56, s90
	s_addc_u32 s39, s63, 0
	s_mov_b32 s57, 1
	v_mov_b32_e32 v16, 0
	s_branch .LBB0_332
